# baseline (speedup 1.0000x reference)
; DI int opq(int x) { asm volatile("" : "+v"(x)); return x; }
; DI f32x16 zero16() { f32x16 z; for (int i = 0; i < 16; ++i) z[i] = 0.f; return z; }
; DI long vt_off(int grp, int b, int head) { return ((long)((grp * BATCH + b) * 4 + head)) * 128 * SEQ; }
; DI int pi32(int r) { return (r & 0x13) | ((r & 4) << 1) | ((r & 8) >> 1); }
; template <int DQK, int MODE>
; DI void attn_core(const u16* __restrict__ Qg, int ldq, const u16* __restrict__ Kg, int ldk, const u16* __restrict__ Vtg,
;                   const u64* __restrict__ maskg, int q0, float scale, char* smem, int* sflags, f32x16 (&o)[4], float& l_run) {
;     ...
;   const int tid = opq(threadIdx.x), lane = tid & 63, wid = tid >> 6, l31 = lane & 31, hh = lane >> 5;
;   const int qrow = q0 + 32 * wid + l31;
;   bf16x8 qf[NKS];
; #pragma unroll
;   for (int ks = 0; ks < NKS; ++ks) qf[ks] = *(const bf16x8*)(Qg + (long)qrow * ldq + ks * 16 + hh * 8);
;   o[0] = zero16(); o[1] = zero16(); o[2] = zero16(); o[3] = zero16();
;   float m_run = -1e30f, r_run = 0.f;
;   l_run = 0.f;
;   const int ntiles = (q0 + 256) >> 6;
;   const int step = (MODE == 2) ? -1 : 1;
;   int tau = (MODE == 2) ? ntiles - 1 : 0;
;   u32x4 rk[NVK], rv[2];
;   auto gload = [&](int tt) {
; #pragma unroll
;     for (int i = 0; i < NVK; ++i) {
;       const int v = tid + NT * i, row = v / VPR, c = v % VPR;
;       rk[i] = *(const u32x4*)(Kg + (long)(tt * 64 + row) * ldk + c * 8);
;     }
; #pragma unroll
;     for (int i = 0; i < 2; ++i) {
;       const int v = tid + NT * i, row = v >> 3, c = v & 7;
;       rv[i] = *(const u32x4*)(Vtg + (long)row * SEQ + tt * 64 + c * 8);
;     }
;   };
;   if (MODE != 2) gload(tau);
;   const float sc = scale * LOG2E;
;   const int krow = pi32(l31);
; __global__ void __launch_bounds__(NT) fwd_megakernel(Params p) {
;     ...
;           const int it = next_item(p.ctr, layer * 8 + 2, &sh_item);
;           if (it >= 512) break;
;           const int t = it >> 1;
;           const int qt = 15 - (t >> 4), bh = t & 15, b = bh >> 2, head = bh & 3;
;           if (it & 1) {
;             const u16* base = p.PROJ + (long)b * SEQ * PW;
;     ...
;             attn_item_simple<128, 1>(p, base + DQ + head * 128, PW, base + DK + head * 128, PW, p.VT + vt_off(3, b, head),
;                                      p.MASK + (long)b * SEQ * 64, b, qt * 256, 0.08838834764831845f, 1536 + head * 128, smem, sflags);
.Lq_common_0:
	ds_read_b32 v0, v1 offset:48
	s_movk_i32 s0, 0x1ff
	s_waitcnt lgkmcnt(0)
	v_cmp_lt_i32_e32 vcc, s0, v0
	v_readfirstlane_b32 s4, v0
	s_mov_b64 s[0:1], -1
	s_cbranch_vccnz .LBB0_148
	s_ashr_i32 s0, s4, 5
	s_sub_i32 s6, 15, s0
	s_bfe_u32 s10, s4, 0x20003
	s_bfe_u32 s9, s4, 0x20001
	s_bitcmp0_b32 s4, 0
	s_mov_b64 s[0:1], -1
	s_cbranch_scc1 .LBB0_167
	s_lshl_b32 s11, s10, 12
	s_mul_i32 s0, s10, 0x2600000
	v_readlane_b32 s16, v249, 6
	v_readlane_b32 s17, v249, 7
	s_add_u32 s0, s16, s0
	s_addc_u32 s1, s17, 0
	s_lshl_b32 s7, s9, 7
	s_lshl_b32 s4, s9, 8
	s_add_u32 s0, s0, s4
	s_addc_u32 s1, s1, 0
	s_add_u32 s14, s0, 0x1000
	s_addc_u32 s15, s1, 0
	s_add_u32 s0, s0, 0x1400
	s_addc_u32 s1, s1, 0
	s_lshl_b32 s5, s10, 22
	s_lshl_b32 s12, s9, 20
	v_readlane_b32 s18, v249, 8
	s_lshl_b32 s4, s10, 21
	s_or_b32 s5, s12, s5
	v_readlane_b32 s19, v249, 9
	v_readlane_b32 s20, v249, 10
	v_readlane_b32 s21, v249, 11
	v_readlane_b32 s22, v249, 12
	v_readlane_b32 s23, v249, 13
	s_add_u32 s5, s18, s5
	s_addc_u32 s12, s19, 0
	v_readlane_b32 s20, v248, 31
	v_mov_b32_e32 v208, v188
	v_mov_b32_e32 v18, v188
	s_add_u32 s16, s5, 0x3000000
	v_readlane_b32 s21, v248, 32
	s_addc_u32 s17, s12, 0
	v_ashrrev_i32_e32 v3, 31, v18
	s_mov_b64 s[12:13], s[20:21]
	v_lshrrev_b32_e32 v3, 28, v3
	s_add_u32 s4, s12, s4
	v_ashrrev_i32_e32 v0, 1, v18
	v_add_u32_e32 v3, v18, v3
	s_addc_u32 s5, s13, 0
	s_lshl_b32 s12, s6, 8
	v_and_b32_e32 v0, 0xffffffe0, v0
	v_ashrrev_i32_e32 v176, 4, v3
	v_and_b32_e32 v3, -16, v3
	v_ashrrev_i32_e32 v8, 3, v18
	v_and_b32_e32 v19, 31, v18
	v_add_u32_e32 v20, s12, v0
	v_lshrrev_b32_e32 v0, 2, v18
	v_sub_u32_e32 v21, v18, v3
	v_add_u32_e32 v3, 0x200, v18
	v_ashrrev_i32_e32 v9, 31, v8
	v_or_b32_e32 v2, v20, v19
	v_mov_b64_e32 v[4:5], s[14:15]
	v_and_b32_e32 v160, 8, v0
	v_ashrrev_i32_e32 v6, 31, v3
	v_lshlrev_b64 v[10:11], 13, v[8:9]
	v_lshlrev_b32_e32 v9, 4, v18
	v_mad_i64_i32 v[4:5], s[14:15], v2, s75, v[4:5]
	v_lshlrev_b32_e32 v0, 1, v160
	v_lshrrev_b32_e32 v6, 28, v6
	v_lshl_add_u64 v[10:11], s[16:17], 0, v[10:11]
	v_and_b32_e32 v12, 0x70, v9
	v_mov_b32_e32 v13, v1
	v_lshl_add_u64 v[4:5], v[4:5], 0, v[0:1]
	v_add_u32_e32 v6, v3, v6
	v_lshl_add_u64 v[162:163], v[10:11], 0, v[12:13]
	v_ashrrev_i32_e32 v10, 3, v3
	global_load_dwordx4 v[140:143], v[4:5], off
	global_load_dwordx4 v[136:139], v[4:5], off offset:32
	global_load_dwordx4 v[132:135], v[4:5], off offset:64
	global_load_dwordx4 v[128:131], v[4:5], off offset:96
	global_load_dwordx4 v[124:127], v[4:5], off offset:128
	global_load_dwordx4 v[120:123], v[4:5], off offset:160
	global_load_dwordx4 v[116:119], v[4:5], off offset:192
	global_load_dwordx4 v[112:115], v[4:5], off offset:224
	v_ashrrev_i32_e32 v177, 4, v6
	v_and_b32_e32 v6, -16, v6
	v_ashrrev_i32_e32 v11, 31, v10
	v_sub_u32_e32 v22, v3, v6
	v_lshlrev_b64 v[14:15], 13, v[10:11]
	v_lshlrev_b32_e32 v6, 3, v22
	v_lshl_add_u64 v[14:15], s[16:17], 0, v[14:15]
	v_lshlrev_b32_e32 v4, 3, v21
	v_ashrrev_i32_e32 v7, 31, v6
	v_lshl_add_u64 v[166:167], v[14:15], 0, v[12:13]
	v_mov_b64_e32 v[14:15], s[0:1]
	v_ashrrev_i32_e32 v5, 31, v4
	v_lshlrev_b64 v[6:7], 1, v[6:7]
	v_mad_i64_i32 v[16:17], s[14:15], v177, s75, v[14:15]
	v_lshlrev_b64 v[4:5], 1, v[4:5]
	v_lshl_add_u64 v[16:17], v[16:17], 0, v[6:7]
	v_mad_i64_i32 v[14:15], s[14:15], v176, s75, v[14:15]
	global_load_dwordx4 v[144:147], v[166:167], off
	global_load_dwordx4 v[148:151], v[162:163], off
	v_lshl_add_u64 v[14:15], v[14:15], 0, v[4:5]
	global_load_dwordx4 v[152:155], v[16:17], off
	global_load_dwordx4 v[156:159], v[14:15], off
	v_lshl_add_u64 v[168:169], s[0:1], 0, v[4:5]
	v_lshl_add_u64 v[170:171], s[0:1], 0, v[6:7]
	s_movk_i32 s0, 0x110
	v_lshlrev_b32_e32 v11, 1, v18
	v_lshrrev_b32_e32 v13, 1, v18
	v_add_u32_e32 v174, 64, v0
	v_mul_lo_u32 v0, v176, s0
	v_ashrrev_i32_e32 v3, 31, v2
	v_and_b32_e32 v9, 19, v18
	v_and_b32_e32 v11, 8, v11
	v_and_b32_e32 v13, 4, v13
	v_add_u32_e32 v17, 64, v0
	v_mul_lo_u32 v0, v177, s0
	s_movk_i32 s0, 0x90
	s_add_i32 s13, s12, 0x100
	v_or3_b32 v9, v9, v11, v13
	v_add_u32_e32 v16, 64, v12
	v_or_b32_e32 v179, 31, v20
	v_lshlrev_b64 v[2:3], 9, v[2:3]
	v_lshlrev_b32_e32 v18, 4, v21
	v_add_u32_e32 v20, 64, v0
	v_lshlrev_b32_e32 v21, 4, v22
	v_mul_lo_u32 v22, v8, s0
	v_mul_lo_u32 v23, v10, s0
	v_mov_b32_e32 v14, v1
	v_mov_b32_e32 v15, v1
	s_lshr_b32 s13, s13, 6
	v_lshl_add_u64 v[164:165], s[4:5], 0, v[2:3]
	v_mul_u32_u24_e32 v178, 0x110, v9
	v_mul_u32_u24_e32 v175, 0x90, v19
	v_mov_b32_e32 v0, v1
	v_mov_b32_e32 v2, v1
	v_mov_b32_e32 v3, v1
	v_mov_b32_e32 v4, v1
	v_mov_b32_e32 v5, v1
	v_mov_b32_e32 v6, v1
	v_mov_b32_e32 v7, v1
	v_mov_b32_e32 v8, v1
	v_mov_b32_e32 v9, v1
	v_mov_b32_e32 v10, v1
	v_mov_b32_e32 v11, v1
	v_mov_b32_e32 v12, v1
	v_mov_b32_e32 v13, v1
	v_add_u32_e32 v180, v17, v18
	v_add_u32_e32 v181, v20, v21
	v_add_u32_e32 v182, v16, v22
	v_add_u32_e32 v183, v16, v23
	v_mov_b64_e32 v[30:31], v[14:15]
	v_mov_b64_e32 v[46:47], v[14:15]
	v_mov_b64_e32 v[62:63], v[14:15]
	v_mov_b64_e32 v[78:79], v[14:15]
	s_add_i32 s14, s13, -1
	s_mov_b32 s15, 0
	v_mov_b32_e32 v184, 0xf149f2ca
	v_mov_b32_e32 v247, 0xff800000
	v_mov_b32_e32 v161, 0
	s_mov_b32 s0, 64
	v_mov_b64_e32 v[172:173], v[164:165]
	v_mov_b64_e32 v[28:29], v[12:13]
	v_mov_b64_e32 v[26:27], v[10:11]
	v_mov_b64_e32 v[24:25], v[8:9]
	v_mov_b64_e32 v[22:23], v[6:7]
	v_mov_b64_e32 v[20:21], v[4:5]
	v_mov_b64_e32 v[18:19], v[2:3]
	v_mov_b64_e32 v[16:17], v[0:1]
	v_mov_b64_e32 v[44:45], v[12:13]
	v_mov_b64_e32 v[42:43], v[10:11]
	v_mov_b64_e32 v[40:41], v[8:9]
	v_mov_b64_e32 v[38:39], v[6:7]
	v_mov_b64_e32 v[36:37], v[4:5]
	v_mov_b64_e32 v[34:35], v[2:3]
	v_mov_b64_e32 v[32:33], v[0:1]
	v_mov_b64_e32 v[60:61], v[12:13]
	v_mov_b64_e32 v[58:59], v[10:11]
	v_mov_b64_e32 v[56:57], v[8:9]
	v_mov_b64_e32 v[54:55], v[6:7]
	v_mov_b64_e32 v[52:53], v[4:5]
	v_mov_b64_e32 v[50:51], v[2:3]
	v_mov_b64_e32 v[48:49], v[0:1]
	v_mov_b64_e32 v[76:77], v[12:13]
	v_mov_b64_e32 v[74:75], v[10:11]
	v_mov_b64_e32 v[72:73], v[8:9]
	v_mov_b64_e32 v[70:71], v[6:7]
	v_mov_b64_e32 v[68:69], v[4:5]
	v_mov_b64_e32 v[66:67], v[2:3]
	v_mov_b64_e32 v[64:65], v[0:1]
	s_mov_b32 s18, 0xefa18f08
	v_readlane_b32 s22, v248, 33
	v_readlane_b32 s23, v248, 34
	s_branch .LBB0_156
; #define MFMA32(a, b, c) __builtin_amdgcn_mfma_f32_32x32x16_bf16((a), (b), (c), 0, 0, 0)
; template <int DQK, int MODE>
; DI void attn_core(const u16* __restrict__ Qg, int ldq, const u16* __restrict__ Kg, int ldk, const u16* __restrict__ Vtg,
;                   const u64* __restrict__ maskg, int q0, float scale, char* smem, int* sflags, f32x16 (&o)[4], float& l_run) {
;     ...
;       const float msc = -m_new * sc;
;       float ls = 0.f;
; #pragma unroll
;       for (int kt = 0; kt < 2; ++kt)
; #pragma unroll
;         for (int i = 0; i < 16; ++i) {
;           float pv = __builtin_amdgcn_exp2f(__builtin_fmaf(s[kt][i], sc, msc));
;           if (MODE == 1) pv = (s[kt][i] > -1e29f) ? pv : 0.f;
;           s[kt][i] = pv;
;           ls += pv;
;         }
;     ...
; #pragma unroll
;     for (int kt = 0; kt < 2; ++kt)
; #pragma unroll
;       for (int sb = 0; sb < 2; ++sb) {
;         const bf16x8 pf = pack8(s[kt][8 * sb + 0], s[kt][8 * sb + 1], s[kt][8 * sb + 2], s[kt][8 * sb + 3],
;                                 s[kt][8 * sb + 4], s[kt][8 * sb + 5], s[kt][8 * sb + 6], s[kt][8 * sb + 7]);
; #pragma unroll
;         for (int t = 0; t < 4; ++t) {
;           const bf16x8 vf = *(const bf16x8*)(Vs + (32 * t + l31) * 72 + 32 * kt + 16 * sb + hh * 8);
;           o[t] = MFMA32(vf, pf, o[t]);
;         }
;       }
.LBB0_154:
	v_mul_f32_e32 v106, 0xbe0293ee, v2
	v_fmamk_f32 v0, v200, 0x3e0293ee, v106
	v_exp_f32_e32 v83, v0
	v_fmamk_f32 v82, v187, 0x3e0293ee, v106
	v_exp_f32_e32 v86, v82
	v_fmamk_f32 v84, v105, 0x3e0293ee, v106
	v_exp_f32_e32 v84, v84
	v_fmamk_f32 v85, v104, 0x3e0293ee, v106
	v_exp_f32_e32 v85, v85
	v_fmamk_f32 v82, v199, 0x3e0293ee, v106
	v_exp_f32_e32 v87, v82
	v_fmamk_f32 v88, v103, 0x3e0293ee, v106
	v_exp_f32_e32 v88, v88
	v_fmamk_f32 v82, v198, 0x3e0293ee, v106
	v_exp_f32_e32 v90, v82
	v_fmamk_f32 v89, v102, 0x3e0293ee, v106
	v_exp_f32_e32 v89, v89
	v_fmamk_f32 v82, v201, 0x3e0293ee, v106
	v_exp_f32_e32 v91, v82
	v_fmamk_f32 v92, v10, 0x3e0293ee, v106
	v_exp_f32_e32 v92, v92
	v_fmamk_f32 v82, v96, 0x3e0293ee, v106
	v_exp_f32_e32 v95, v82
	v_add_f32_e32 v0, 0, v83
	v_add_f32_e32 v0, v86, v0
	v_fmamk_f32 v82, v186, 0x3e0293ee, v106
	v_exp_f32_e32 v96, v82
	v_add_f32_e32 v0, v87, v0
	v_add_f32_e32 v0, v90, v0
	v_fmamk_f32 v82, v97, 0x3e0293ee, v106
	v_exp_f32_e32 v97, v82
	v_add_f32_e32 v0, v91, v0
	v_add_f32_e32 v0, v95, v0
	v_fmamk_f32 v82, v185, 0x3e0293ee, v106
	v_exp_f32_e32 v82, v82
	v_add_f32_e32 v0, v96, v0
	v_add_f32_e32 v0, v97, v0
	v_add_f32_e32 v0, v82, v0
	v_mov_b32_e32 v184, v2
	v_add_f32_e32 v0, v84, v0
	s_nop 0
	v_add_f32_e32 v0, v85, v0
	s_nop 0
	v_add_f32_e32 v0, v88, v0
	s_nop 0
	v_fmamk_f32 v10, v100, 0x3e0293ee, v106
	v_exp_f32_e32 v93, v10
	v_add_f32_e32 v0, v89, v0
	v_add_f32_e32 v0, v92, v0
	v_fmamk_f32 v10, v11, 0x3e0293ee, v106
	v_exp_f32_e32 v94, v10
	v_fmamk_f32 v11, v99, 0x3e0293ee, v106
	v_exp_f32_e32 v11, v11
	v_fmamk_f32 v10, v101, 0x3e0293ee, v106
	v_exp_f32_e32 v10, v10
	v_add_f32_e32 v0, v93, v0
	v_add_f32_e32 v0, v94, v0
	v_fmamk_f32 v99, v12, 0x3e0293ee, v106
	v_exp_f32_e32 v12, v99
	v_add_f32_e32 v0, v10, v0
	v_add_f32_e32 v0, v11, v0
	v_fmamk_f32 v99, v13, 0x3e0293ee, v106
	v_exp_f32_e32 v13, v99
	v_add_f32_e32 v0, v12, v0
	s_nop 0
	v_fmamk_f32 v99, v14, 0x3e0293ee, v106
	v_exp_f32_e32 v14, v99
	v_add_f32_e32 v0, v13, v0
	s_nop 0
	v_fmamk_f32 v99, v15, 0x3e0293ee, v106
	v_exp_f32_e32 v15, v99
	v_add_f32_e32 v0, v14, v0
	s_nop 0
	v_fmamk_f32 v99, v80, 0x3e0293ee, v106
	v_exp_f32_e32 v80, v99
	v_add_f32_e32 v0, v15, v0
	s_nop 0
	v_fmamk_f32 v99, v81, 0x3e0293ee, v106
	v_exp_f32_e32 v81, v99
	v_add_f32_e32 v0, v80, v0
	s_nop 0
	v_add_f32_e32 v99, v81, v0
	v_fmamk_f32 v0, v98, 0x3e0293ee, v106
	v_exp_f32_e32 v0, v0
	s_nop 1
	v_add_f32_e32 v98, v0, v99
	v_fmamk_f32 v99, v3, 0x3e0293ee, v106
	v_exp_f32_e32 v3, v99
	s_nop 1
	v_fmamk_f32 v99, v4, 0x3e0293ee, v106
	v_exp_f32_e32 v4, v99
	v_add_f32_e32 v98, v3, v98
	s_nop 0
	v_fmamk_f32 v99, v5, 0x3e0293ee, v106
	v_exp_f32_e32 v5, v99
	v_add_f32_e32 v98, v4, v98
	s_nop 0
	v_fmamk_f32 v99, v6, 0x3e0293ee, v106
	v_exp_f32_e32 v6, v99
	v_add_f32_e32 v98, v5, v98
	s_nop 0
	v_fmamk_f32 v99, v7, 0x3e0293ee, v106
	v_exp_f32_e32 v7, v99
	v_add_f32_e32 v98, v6, v98
	s_nop 0
	v_fmamk_f32 v99, v8, 0x3e0293ee, v106
	v_exp_f32_e32 v8, v99
	v_fmac_f32_e32 v106, 0x3e0293ee, v9
	v_add_f32_e32 v98, v7, v98
	v_exp_f32_e32 v9, v106
	v_add_f32_e32 v98, v8, v98
	s_nop 0
	v_add_f32_e32 v98, v9, v98
	v_add_f32_e32 v161, v98, v161
	v_cvt_pk_bf16_f32 v98, v83, v86
	v_cvt_pk_bf16_f32 v99, v87, v90
	v_cvt_pk_bf16_f32 v100, v91, v95
	v_cvt_pk_bf16_f32 v101, v96, v97
	s_nop 1
	v_add_u32_e32 v83, v174, v175
	ds_read_b128 v[198:201], v83 offset:17408
	ds_read_b128 v[202:205], v83 offset:22016
	ds_read_b128 v[210:213], v83 offset:26624
	ds_read_b128 v[214:217], v83 offset:31232
	ds_read_b128 v[218:221], v83 offset:17440
	ds_read_b128 v[226:229], v83 offset:22048
	s_waitcnt lgkmcnt(5)
	v_mfma_f32_32x32x16_bf16 v[64:79], v[198:201], v[98:101], v[64:79]
	ds_read_b128 v[198:201], v83 offset:26656
	s_waitcnt lgkmcnt(5)
	v_mfma_f32_32x32x16_bf16 v[48:63], v[202:205], v[98:101], v[48:63]
	ds_read_b128 v[202:205], v83 offset:31264
	s_waitcnt lgkmcnt(5)
	v_mfma_f32_32x32x16_bf16 v[32:47], v[210:213], v[98:101], v[32:47]
	ds_read_b128 v[210:213], v83 offset:17472
	s_waitcnt lgkmcnt(5)
	v_mfma_f32_32x32x16_bf16 v[16:31], v[214:217], v[98:101], v[16:31]
	ds_read_b128 v[214:217], v83 offset:22080
	v_cvt_pk_bf16_f32 v96, v82, v84
	v_cvt_pk_bf16_f32 v97, v85, v88
	v_cvt_pk_bf16_f32 v98, v89, v92
	v_cvt_pk_bf16_f32 v99, v93, v94
	s_nop 1
	s_waitcnt lgkmcnt(5)
	v_mfma_f32_32x32x16_bf16 v[64:79], v[218:221], v[96:99], v[64:79]
	ds_read_b128 v[218:221], v83 offset:26688
	s_waitcnt lgkmcnt(5)
	v_mfma_f32_32x32x16_bf16 v[48:63], v[226:229], v[96:99], v[48:63]
	ds_read_b128 v[226:229], v83 offset:31296
	s_waitcnt lgkmcnt(5)
	v_mfma_f32_32x32x16_bf16 v[32:47], v[198:201], v[96:99], v[32:47]
	ds_read_b128 v[198:201], v83 offset:17504
	s_waitcnt lgkmcnt(5)
	v_mfma_f32_32x32x16_bf16 v[16:31], v[202:205], v[96:99], v[16:31]
	ds_read_b128 v[202:205], v83 offset:22112
	v_cvt_pk_bf16_f32 v84, v10, v11
	v_cvt_pk_bf16_f32 v85, v12, v13
	v_cvt_pk_bf16_f32 v86, v14, v15
	v_cvt_pk_bf16_f32 v87, v80, v81
	s_nop 1
	s_waitcnt lgkmcnt(5)
	v_mfma_f32_32x32x16_bf16 v[64:79], v[210:213], v[84:87], v[64:79]
	ds_read_b128 v[210:213], v83 offset:26720
	s_waitcnt lgkmcnt(5)
	v_mfma_f32_32x32x16_bf16 v[48:63], v[214:217], v[84:87], v[48:63]
	ds_read_b128 v[214:217], v83 offset:31328
	s_waitcnt lgkmcnt(5)
	v_mfma_f32_32x32x16_bf16 v[32:47], v[218:221], v[84:87], v[32:47]
	s_waitcnt lgkmcnt(4)
	v_mfma_f32_32x32x16_bf16 v[16:31], v[226:229], v[84:87], v[16:31]
	v_cvt_pk_bf16_f32 v10, v0, v3
	v_cvt_pk_bf16_f32 v11, v4, v5
	v_cvt_pk_bf16_f32 v12, v6, v7
	v_cvt_pk_bf16_f32 v13, v8, v9
	s_nop 1
	s_waitcnt lgkmcnt(3)
	v_mfma_f32_32x32x16_bf16 v[64:79], v[198:201], v[10:13], v[64:79]
	s_waitcnt lgkmcnt(2)
	v_mfma_f32_32x32x16_bf16 v[48:63], v[202:205], v[10:13], v[48:63]
	s_waitcnt lgkmcnt(1)
	v_mfma_f32_32x32x16_bf16 v[32:47], v[210:213], v[10:13], v[32:47]
	s_waitcnt lgkmcnt(0)
	v_mfma_f32_32x32x16_bf16 v[16:31], v[214:217], v[10:13], v[16:31]

; template <int DQK, int MODE>
; DI void attn_core(const u16* __restrict__ Qg, int ldq, const u16* __restrict__ Kg, int ldk, const u16* __restrict__ Vtg,
;                   const u64* __restrict__ maskg, int q0, float scale, char* smem, int* sflags, f32x16 (&o)[4], float& l_run) {
;     ...
;   for (int it = 0; it < ntiles; ++it, tau += step) {
;     __syncthreads();
;     if (MODE == 2 && it > 0) {
;       if (!(sflags[0] | sflags[1] | sflags[2] | sflags[3] | sflags[4] | sflags[5] | sflags[6] | sflags[7])) break;
;     }
;     if (MODE == 2) gload(tau);
; #pragma unroll
;     for (int i = 0; i < NVK; ++i) {
;       const int v = tid + NT * i, row = v / VPR, c = v % VPR;
;       *(u32x4*)(Ks + row * KSTR + c * 8) = rk[i];
;     }
; #pragma unroll
;     for (int i = 0; i < 2; ++i) {
;       const int v = tid + NT * i, row = v >> 3, c = v & 7;
;       *(u32x4*)(Vs + row * 72 + c * 8) = rv[i];
;     }
;     __syncthreads();
;     if (MODE != 2 && it + 1 < ntiles) gload(tau + step);
;     if (tau * 64 > q0 + 32 * wid + 31) {
;       if (MODE == 2 && lane == 0) sflags[wid] = 1;
;       continue;
;     }
.LBB0_156:
	v_add_u32_e32 v0, s0, v176
	v_mad_i64_i32 v[2:3], s[4:5], v0, s75, v[168:169]
	v_add_u32_e32 v0, s0, v177
	v_mad_i64_i32 v[4:5], s[4:5], v0, s75, v[170:171]
	s_ashr_i32 s1, s0, 31
	s_lshl_b64 s[4:5], s[0:1], 1
	s_nop 0
	s_waitcnt vmcnt(0)
	ds_write_b128 v180, v[156:159]
	ds_write_b128 v181, v[152:155]
	ds_write_b128 v182, v[148:151] offset:17408
	ds_write_b128 v183, v[144:147] offset:17408
	s_waitcnt lgkmcnt(0)
	global_load_dwordx4 v[156:159], v[2:3], off
	global_load_dwordx4 v[152:155], v[4:5], off
	v_lshl_add_u64 v[2:3], v[162:163], 0, s[4:5]
	v_lshl_add_u64 v[4:5], v[166:167], 0, s[4:5]
	global_load_dwordx4 v[148:151], v[2:3], off
	global_load_dwordx4 v[144:147], v[4:5], off
	s_sub_i32 s1, s0, 64
	s_barrier
	v_cmp_le_i32_e32 vcc, s1, v179
	s_and_saveexec_b64 s[4:5], vcc
	s_cbranch_execz .LBB0_155
; #define MFMA32(a, b, c) __builtin_amdgcn_mfma_f32_32x32x16_bf16((a), (b), (c), 0, 0, 0)
; DI f32x16 zero16() { f32x16 z; for (int i = 0; i < 16; ++i) z[i] = 0.f; return z; }
; template <int DQK, int MODE>
; DI void attn_core(const u16* __restrict__ Qg, int ldq, const u16* __restrict__ Kg, int ldk, const u16* __restrict__ Vtg,
;                   const u64* __restrict__ maskg, int q0, float scale, char* smem, int* sflags, f32x16 (&o)[4], float& l_run) {
;     ...
;     u64 mbits = 0;
;     if (MODE == 1) mbits = maskg[(long)qrow * 64 + tau] >> (8 * hh);
;     f32x16 s[2];
;     s[0] = zero16(); s[1] = zero16();
; #pragma unroll
;     for (int kt = 0; kt < 2; ++kt)
; #pragma unroll
;       for (int ks = 0; ks < NKS; ++ks) {
;         const bf16x8 kf = *(const bf16x8*)(Ks + (32 * kt + krow) * KSTR + ks * 16 + hh * 8);
;         s[kt] = MFMA32(kf, qf[ks], s[kt]);
;       }
;     const int kbase = tau * 64 + 8 * hh;
;     if (MODE == 0 || MODE == 1) {
;       const bool need_mask = (MODE == 1) || (tau * 64 + 63 > q0 + 32 * wid);
;       float mx = -1e30f;
;       if (need_mask) {
; #pragma unroll
;         for (int kt = 0; kt < 2; ++kt)
; #pragma unroll
;           for (int i = 0; i < 16; ++i) {
;             bool valid;
;             if (MODE == 1) valid = (mbits >> (32 * kt + 16 * (i >> 3) + (i & 7))) & 1ull;
;             else valid = (kbase + 32 * kt + 16 * (i >> 3) + (i & 7)) <= qrow;
;             s[kt][i] = valid ? s[kt][i] : -1e30f;
;           }
;       }
; #pragma unroll
;       for (int kt = 0; kt < 2; ++kt)
; #pragma unroll
;         for (int i = 0; i < 16; ++i) mx = fmaxf(mx, s[kt][i]);
;       mx = fmaxf(mx, __shfl_xor(mx, 32));
;       const float m_new = fmaxf(m_run, mx);
;       const float alpha = __builtin_amdgcn_exp2f((m_run - m_new) * sc);
;       m_run = m_new;
	v_add_u32_e32 v0, v174, v178
	global_load_dwordx2 v[10:11], v[172:173], off
	ds_read_b128 v[12:15], v0
	ds_read_b128 v[202:205], v0 offset:32
	ds_read_b128 v[210:213], v0 offset:64
	ds_read_b128 v[214:217], v0 offset:96
	ds_read_b128 v[218:221], v0 offset:128
	ds_read_b128 v[226:229], v0 offset:160
	s_waitcnt lgkmcnt(5)
	v_mfma_f32_32x32x16_bf16 v[96:111], v[12:15], v[140:143], 0
	ds_read_b128 v[12:15], v0 offset:192
	s_waitcnt lgkmcnt(5)
	v_mfma_f32_32x32x16_bf16 v[96:111], v[202:205], v[136:139], v[96:111]
	ds_read_b128 v[202:205], v0 offset:224
	s_waitcnt vmcnt(0)
	v_lshrrev_b64 v[8:9], v160, v[10:11]
	s_waitcnt lgkmcnt(5)
	v_mfma_f32_32x32x16_bf16 v[96:111], v[210:213], v[132:135], v[96:111]
	ds_read_b128 v[210:213], v0 offset:8704
	s_waitcnt lgkmcnt(5)
	v_mfma_f32_32x32x16_bf16 v[96:111], v[214:217], v[128:131], v[96:111]
	ds_read_b128 v[214:217], v0 offset:8736
	s_waitcnt lgkmcnt(5)
	v_mfma_f32_32x32x16_bf16 v[96:111], v[218:221], v[124:127], v[96:111]
	ds_read_b128 v[218:221], v0 offset:8768
	s_waitcnt lgkmcnt(5)
	v_mfma_f32_32x32x16_bf16 v[96:111], v[226:229], v[120:123], v[96:111]
	ds_read_b128 v[226:229], v0 offset:8800
	s_waitcnt lgkmcnt(5)
	v_mfma_f32_32x32x16_bf16 v[96:111], v[12:15], v[116:119], v[96:111]
	ds_read_b128 v[12:15], v0 offset:8832
	s_waitcnt lgkmcnt(5)
	v_mfma_f32_32x32x16_bf16 v[96:111], v[202:205], v[112:115], v[96:111]
	ds_read_b128 v[202:205], v0 offset:8864
	s_waitcnt lgkmcnt(5)
	v_mfma_f32_32x32x16_bf16 v[80:95], v[210:213], v[140:143], 0
	ds_read_b128 v[210:213], v0 offset:8896
	s_waitcnt lgkmcnt(5)
	v_mfma_f32_32x32x16_bf16 v[80:95], v[214:217], v[136:139], v[80:95]
	ds_read_b128 v[214:217], v0 offset:8928
	s_waitcnt lgkmcnt(5)
	v_mfma_f32_32x32x16_bf16 v[80:95], v[218:221], v[132:135], v[80:95]
	s_waitcnt lgkmcnt(4)
	v_mfma_f32_32x32x16_bf16 v[80:95], v[226:229], v[128:131], v[80:95]
	s_waitcnt lgkmcnt(3)
	v_mfma_f32_32x32x16_bf16 v[80:95], v[12:15], v[124:127], v[80:95]
	s_waitcnt lgkmcnt(2)
	v_mfma_f32_32x32x16_bf16 v[80:95], v[202:205], v[120:123], v[80:95]
	s_waitcnt lgkmcnt(1)
	v_mfma_f32_32x32x16_bf16 v[80:95], v[210:213], v[116:119], v[80:95]
	v_lshrrev_b32_e32 v0, v160, v10
	v_and_b32_e32 v0, 1, v0
	v_cmp_eq_u32_e32 vcc, 1, v0
	v_and_b32_e32 v0, 2, v8
	s_nop 0
	v_cndmask_b32_e32 v200, v247, v96, vcc
	v_cmp_ne_u32_e32 vcc, 0, v0
	v_and_b32_e32 v0, 4, v8
	s_waitcnt lgkmcnt(0)
	v_mfma_f32_32x32x16_bf16 v[80:95], v[214:217], v[112:115], v[80:95]
	v_cndmask_b32_e32 v187, v247, v97, vcc
	v_cmp_ne_u32_e32 vcc, 0, v0
	v_and_b32_e32 v0, 8, v8
	v_mbcnt_hi_u32_b32 v2, -1, v223
	v_cndmask_b32_e32 v199, v247, v98, vcc
	v_cmp_ne_u32_e32 vcc, 0, v0
	v_and_b32_e32 v0, 16, v8
	s_nop 0
	v_cndmask_b32_e32 v198, v247, v99, vcc
	v_cmp_ne_u32_e32 vcc, 0, v0
	v_and_b32_e32 v0, 32, v8
	s_nop 0
	v_cndmask_b32_e32 v201, v247, v100, vcc
	v_cmp_ne_u32_e32 vcc, 0, v0
	v_and_b32_e32 v0, 64, v8
	s_nop 0
	v_cndmask_b32_e32 v96, v247, v101, vcc
	v_cmp_ne_u32_e32 vcc, 0, v0
	v_and_b32_e32 v0, 0x80, v8
	s_nop 0
	v_cndmask_b32_e32 v186, v247, v102, vcc
	v_cmp_ne_u32_e32 vcc, 0, v0
	v_and_b32_e32 v0, 0x10000, v8
	s_nop 0
	v_cndmask_b32_e32 v97, v247, v103, vcc
	v_cmp_ne_u32_e32 vcc, 0, v0
	v_and_b32_e32 v0, 0x20000, v8
	s_nop 0
	v_cndmask_b32_e32 v185, v247, v104, vcc
	v_cmp_ne_u32_e32 vcc, 0, v0
	v_and_b32_e32 v0, 0x40000, v8
	s_nop 0
	v_cndmask_b32_e32 v105, v247, v105, vcc
	v_cmp_ne_u32_e32 vcc, 0, v0
	v_and_b32_e32 v0, 0x80000, v8
	s_nop 0
	v_cndmask_b32_e32 v104, v247, v106, vcc
	v_cmp_ne_u32_e32 vcc, 0, v0
	v_and_b32_e32 v0, 0x100000, v8
	s_nop 0
	v_cndmask_b32_e32 v103, v247, v107, vcc
	v_cmp_ne_u32_e32 vcc, 0, v0
	v_and_b32_e32 v0, 0x200000, v8
	s_nop 0
	v_cndmask_b32_e32 v102, v247, v108, vcc
	v_cmp_ne_u32_e32 vcc, 0, v0
	v_and_b32_e32 v0, 0x400000, v8
	s_nop 0
	v_cndmask_b32_e32 v10, v247, v109, vcc
	v_cmp_ne_u32_e32 vcc, 0, v0
	v_and_b32_e32 v0, 0x800000, v8
	s_nop 0
	v_cndmask_b32_e32 v100, v247, v110, vcc
	v_cmp_ne_u32_e32 vcc, 0, v0
	v_and_b32_e32 v0, 1, v9
	s_nop 0
	v_cndmask_b32_e32 v11, v247, v111, vcc
	v_cmp_eq_u32_e32 vcc, 1, v0
	v_and_b32_e32 v0, 2, v9
	s_nop 0
	v_cndmask_b32_e32 v101, v247, v80, vcc
	v_cmp_ne_u32_e32 vcc, 0, v0
	v_and_b32_e32 v0, 4, v9
	s_nop 0
	v_cndmask_b32_e32 v99, v247, v81, vcc
	v_cmp_ne_u32_e32 vcc, 0, v0
	v_and_b32_e32 v0, 8, v9
	s_nop 0
	v_cndmask_b32_e32 v12, v247, v82, vcc
	v_cmp_ne_u32_e32 vcc, 0, v0
	v_and_b32_e32 v0, 16, v9
	v_xor_b32_e32 v82, 32, v2
	v_cndmask_b32_e32 v13, v247, v83, vcc
	v_cmp_ne_u32_e32 vcc, 0, v0
	v_and_b32_e32 v0, 32, v9
	v_and_b32_e32 v83, 64, v2
	v_cndmask_b32_e32 v14, v247, v84, vcc
	v_cmp_ne_u32_e32 vcc, 0, v0
	v_and_b32_e32 v0, 64, v9
	v_add_u32_e32 v83, 64, v83
	v_cndmask_b32_e32 v15, v247, v85, vcc
	v_cmp_ne_u32_e32 vcc, 0, v0
	v_and_b32_e32 v0, 0x80, v9
	s_nop 0
	v_cndmask_b32_e32 v80, v247, v86, vcc
	v_cmp_ne_u32_e32 vcc, 0, v0
	v_and_b32_e32 v0, 0x10000, v9
	s_nop 0
	v_cndmask_b32_e32 v81, v247, v87, vcc
	v_cmp_ne_u32_e32 vcc, 0, v0
	v_and_b32_e32 v0, 0x20000, v9
	s_nop 0
	v_cndmask_b32_e32 v98, v247, v88, vcc
	v_cmp_ne_u32_e32 vcc, 0, v0
	v_and_b32_e32 v0, 0x40000, v9
	s_nop 0
	v_cndmask_b32_e32 v3, v247, v89, vcc
	v_cmp_ne_u32_e32 vcc, 0, v0
	v_and_b32_e32 v0, 0x80000, v9
	s_nop 0
	v_cndmask_b32_e32 v4, v247, v90, vcc
	v_cmp_ne_u32_e32 vcc, 0, v0
	v_and_b32_e32 v0, 0x100000, v9
	s_nop 0
	v_cndmask_b32_e32 v5, v247, v91, vcc
	v_cmp_ne_u32_e32 vcc, 0, v0
	v_and_b32_e32 v0, 0x200000, v9
	s_nop 0
	v_cndmask_b32_e32 v6, v247, v92, vcc
	v_cmp_ne_u32_e32 vcc, 0, v0
	v_and_b32_e32 v0, 0x400000, v9
	s_nop 0
	v_cndmask_b32_e32 v7, v247, v93, vcc
	v_cmp_ne_u32_e32 vcc, 0, v0
	v_and_b32_e32 v0, 0x800000, v9
	s_nop 0
	v_cndmask_b32_e32 v8, v247, v94, vcc
	v_cmp_ne_u32_e32 vcc, 0, v0
	v_max3_f32 v0, v200, s58, v187
	v_max3_f32 v0, v0, v199, v198
	v_max3_f32 v0, v0, v201, v96
	v_max3_f32 v0, v0, v186, v97
	v_max3_f32 v0, v0, v185, v105
	v_max3_f32 v0, v0, v104, v103
	v_max3_f32 v0, v0, v102, v10
	v_max3_f32 v0, v0, v100, v11
	v_max3_f32 v0, v0, v101, v99
	v_max3_f32 v0, v0, v12, v13
	v_max3_f32 v0, v0, v14, v15
	v_max3_f32 v0, v0, v80, v81
	v_max3_f32 v0, v0, v98, v3
	v_cndmask_b32_e32 v9, v247, v95, vcc
	v_max3_f32 v0, v0, v4, v5
	v_cmp_lt_i32_e32 vcc, v82, v83
	v_max3_f32 v0, v0, v6, v7
	v_max3_f32 v0, v0, v8, v9
	v_cndmask_b32_e32 v2, v2, v82, vcc
	v_lshlrev_b32_e32 v2, 2, v2
	ds_bpermute_b32 v2, v2, v0
	s_waitcnt lgkmcnt(0)
	v_max3_f32 v2, v184, v0, v2
	v_sub_f32_e32 v0, v2, v184
	v_mul_f32_e32 v0, 0x3e0293ee, v0
	v_cmp_lt_f32_e32 vcc, 0x41000000, v0
	s_cbranch_vccnz .Llazy_keep_1
	v_mov_b32_e32 v2, v184

; template <int DQK, int MODE>
; DI void attn_core(const u16* __restrict__ Qg, int ldq, const u16* __restrict__ Kg, int ldk, const u16* __restrict__ Vtg,
;                   const u64* __restrict__ maskg, int q0, float scale, char* smem, int* sflags, f32x16 (&o)[4], float& l_run) {
;     ...
;   for (int it = 0; it < ntiles; ++it, tau += step) {
;     __syncthreads();
;     if (MODE == 2 && it > 0) {
;       if (!(sflags[0] | sflags[1] | sflags[2] | sflags[3] | sflags[4] | sflags[5] | sflags[6] | sflags[7])) break;
;     }
;     if (MODE == 2) gload(tau);
; #pragma unroll
;     for (int i = 0; i < NVK; ++i) {
;       const int v = tid + NT * i, row = v / VPR, c = v % VPR;
;       *(u32x4*)(Ks + row * KSTR + c * 8) = rk[i];
;     }
; #pragma unroll
;     for (int i = 0; i < 2; ++i) {
;       const int v = tid + NT * i, row = v >> 3, c = v & 7;
;       *(u32x4*)(Vs + row * 72 + c * 8) = rv[i];
;     }
;     __syncthreads();
;     if (MODE != 2 && it + 1 < ntiles) gload(tau + step);
;     if (tau * 64 > q0 + 32 * wid + 31) {
;       if (MODE == 2 && lane == 0) sflags[wid] = 1;
;       continue;
;     }
.LBB0_159:
	s_lshl_b32 s0, s14, 6
	v_cmp_le_i32_e32 vcc, s0, v179
	s_nop 0
	s_waitcnt vmcnt(3)
	ds_write_b128 v180, v[156:159]
	s_waitcnt vmcnt(2)
	ds_write_b128 v181, v[152:155]
	s_waitcnt vmcnt(1)
	ds_write_b128 v182, v[148:151] offset:17408
	s_waitcnt vmcnt(0)
	ds_write_b128 v183, v[144:147] offset:17408
	s_waitcnt lgkmcnt(0)
	s_barrier
	s_and_saveexec_b64 s[0:1], vcc
	s_xor_b64 s[0:1], exec, s[0:1]
	s_cbranch_execz .LBB0_164
; #define MFMA32(a, b, c) __builtin_amdgcn_mfma_f32_32x32x16_bf16((a), (b), (c), 0, 0, 0)
; DI f32x16 zero16() { f32x16 z; for (int i = 0; i < 16; ++i) z[i] = 0.f; return z; }
; template <int DQK, int MODE>
; DI void attn_core(const u16* __restrict__ Qg, int ldq, const u16* __restrict__ Kg, int ldk, const u16* __restrict__ Vtg,
;                   const u64* __restrict__ maskg, int q0, float scale, char* smem, int* sflags, f32x16 (&o)[4], float& l_run) {
;     ...
;     u64 mbits = 0;
;     if (MODE == 1) mbits = maskg[(long)qrow * 64 + tau] >> (8 * hh);
;     f32x16 s[2];
;     s[0] = zero16(); s[1] = zero16();
; #pragma unroll
;     for (int kt = 0; kt < 2; ++kt)
; #pragma unroll
;       for (int ks = 0; ks < NKS; ++ks) {
;         const bf16x8 kf = *(const bf16x8*)(Ks + (32 * kt + krow) * KSTR + ks * 16 + hh * 8);
;         s[kt] = MFMA32(kf, qf[ks], s[kt]);
;       }
;     const int kbase = tau * 64 + 8 * hh;
;     if (MODE == 0 || MODE == 1) {
;       const bool need_mask = (MODE == 1) || (tau * 64 + 63 > q0 + 32 * wid);
;       float mx = -1e30f;
;       if (need_mask) {
; #pragma unroll
;         for (int kt = 0; kt < 2; ++kt)
; #pragma unroll
;           for (int i = 0; i < 16; ++i) {
;             bool valid;
;             if (MODE == 1) valid = (mbits >> (32 * kt + 16 * (i >> 3) + (i & 7))) & 1ull;
;             else valid = (kbase + 32 * kt + 16 * (i >> 3) + (i & 7)) <= qrow;
;             s[kt][i] = valid ? s[kt][i] : -1e30f;
;           }
;       }
; #pragma unroll
;       for (int kt = 0; kt < 2; ++kt)
; #pragma unroll
;         for (int i = 0; i < 16; ++i) mx = fmaxf(mx, s[kt][i]);
;       mx = fmaxf(mx, __shfl_xor(mx, 32));
;       const float m_new = fmaxf(m_run, mx);
;       const float alpha = __builtin_amdgcn_exp2f((m_run - m_new) * sc);
;       m_run = m_new;
	v_readlane_b32 s4, v249, 29
	v_readlane_b32 s5, v249, 30
	s_mov_b32 s15, s5
	s_add_i32 s14, s13, -2
	v_lshl_add_u64 v[2:3], s[14:15], 3, v[164:165]
	v_add_u32_e32 v0, v174, v178
	global_load_dwordx2 v[10:11], v[2:3], off offset:8
	ds_read_b128 v[12:15], v0
	ds_read_b128 v[144:147], v0 offset:32
	ds_read_b128 v[148:151], v0 offset:64
	ds_read_b128 v[152:155], v0 offset:96
	ds_read_b128 v[156:159], v0 offset:128
	ds_read_b128 v[162:165], v0 offset:160
	s_waitcnt lgkmcnt(5)
	v_mfma_f32_32x32x16_bf16 v[80:95], v[12:15], v[140:143], 0
	ds_read_b128 v[12:15], v0 offset:192
	v_writelane_b32 v249, s4, 29
	s_nop 1
	v_writelane_b32 v249, s5, 30
	s_waitcnt lgkmcnt(5)
	v_mfma_f32_32x32x16_bf16 v[80:95], v[144:147], v[136:139], v[80:95]
	ds_read_b128 v[144:147], v0 offset:224
	s_waitcnt lgkmcnt(5)
	v_mfma_f32_32x32x16_bf16 v[80:95], v[148:151], v[132:135], v[80:95]
	ds_read_b128 v[148:151], v0 offset:8704
	s_waitcnt lgkmcnt(5)
	v_mfma_f32_32x32x16_bf16 v[80:95], v[152:155], v[128:131], v[80:95]
	ds_read_b128 v[152:155], v0 offset:8736
	s_waitcnt lgkmcnt(5)
	v_mfma_f32_32x32x16_bf16 v[80:95], v[156:159], v[124:127], v[80:95]
	ds_read_b128 v[156:159], v0 offset:8768
	s_waitcnt lgkmcnt(5)
	v_mfma_f32_32x32x16_bf16 v[80:95], v[162:165], v[120:123], v[80:95]
	ds_read_b128 v[162:165], v0 offset:8800
	s_waitcnt lgkmcnt(5)
	v_mfma_f32_32x32x16_bf16 v[80:95], v[12:15], v[116:119], v[80:95]
	ds_read_b128 v[12:15], v0 offset:8832
	s_waitcnt lgkmcnt(5)
	v_mfma_f32_32x32x16_bf16 v[80:95], v[144:147], v[112:115], v[80:95]
	ds_read_b128 v[144:147], v0 offset:8864
	s_waitcnt lgkmcnt(5)
	v_mfma_f32_32x32x16_bf16 v[96:111], v[148:151], v[140:143], 0
	ds_read_b128 v[148:151], v0 offset:8896
	s_waitcnt lgkmcnt(5)
	v_mfma_f32_32x32x16_bf16 v[96:111], v[152:155], v[136:139], v[96:111]
	ds_read_b128 v[152:155], v0 offset:8928
	s_waitcnt lgkmcnt(5)
	v_mfma_f32_32x32x16_bf16 v[96:111], v[156:159], v[132:135], v[96:111]
	s_waitcnt lgkmcnt(4)
	v_mfma_f32_32x32x16_bf16 v[96:111], v[162:165], v[128:131], v[96:111]
	s_waitcnt lgkmcnt(3)
	v_mfma_f32_32x32x16_bf16 v[96:111], v[12:15], v[124:127], v[96:111]
	s_waitcnt lgkmcnt(2)
	v_mfma_f32_32x32x16_bf16 v[96:111], v[144:147], v[120:123], v[96:111]
	s_waitcnt lgkmcnt(1)
	v_mfma_f32_32x32x16_bf16 v[96:111], v[148:151], v[116:119], v[96:111]
	s_waitcnt vmcnt(0)
	v_lshrrev_b32_e32 v0, v160, v10
	v_and_b32_e32 v0, 1, v0
	v_cmp_eq_u32_e32 vcc, 1, v0
	s_nop 1
	v_cndmask_b32_e32 v121, v247, v80, vcc
	s_waitcnt lgkmcnt(0)
	v_mfma_f32_32x32x16_bf16 v[96:111], v[152:155], v[112:115], v[96:111]
	v_lshrrev_b64 v[2:3], v160, v[10:11]
	v_and_b32_e32 v0, 2, v2
	v_cmp_ne_u32_e32 vcc, 0, v0
	v_and_b32_e32 v0, 4, v2
	s_nop 0
	v_cndmask_b32_e32 v118, v247, v81, vcc
	v_cmp_ne_u32_e32 vcc, 0, v0
	v_and_b32_e32 v0, 8, v2
	s_nop 0
	v_cndmask_b32_e32 v120, v247, v82, vcc
	v_cmp_ne_u32_e32 vcc, 0, v0
	v_and_b32_e32 v0, 16, v2
	s_nop 0
	v_cndmask_b32_e32 v119, v247, v83, vcc
	v_cmp_ne_u32_e32 vcc, 0, v0
	v_and_b32_e32 v0, 32, v2
	s_nop 0
	v_cndmask_b32_e32 v122, v247, v84, vcc
	v_cmp_ne_u32_e32 vcc, 0, v0
	v_and_b32_e32 v0, 64, v2
	s_nop 0
	v_cndmask_b32_e32 v116, v247, v85, vcc
	v_cmp_ne_u32_e32 vcc, 0, v0
	v_and_b32_e32 v0, 0x80, v2
	s_nop 0
	v_cndmask_b32_e32 v117, v247, v86, vcc
	v_cmp_ne_u32_e32 vcc, 0, v0
	v_and_b32_e32 v0, 0x10000, v2
	s_nop 0
	v_cndmask_b32_e32 v115, v247, v87, vcc
	v_cmp_ne_u32_e32 vcc, 0, v0
	v_and_b32_e32 v0, 0x20000, v2
	s_nop 0
	v_cndmask_b32_e32 v85, v247, v88, vcc
	v_cmp_ne_u32_e32 vcc, 0, v0
	v_and_b32_e32 v0, 0x40000, v2
	s_nop 0
	v_cndmask_b32_e32 v87, v247, v89, vcc
	v_cmp_ne_u32_e32 vcc, 0, v0
	v_and_b32_e32 v0, 0x80000, v2
	s_nop 0
	v_cndmask_b32_e32 v88, v247, v90, vcc
	v_cmp_ne_u32_e32 vcc, 0, v0
	v_and_b32_e32 v0, 0x100000, v2
	s_nop 0
	v_cndmask_b32_e32 v91, v247, v91, vcc
	v_cmp_ne_u32_e32 vcc, 0, v0
	v_and_b32_e32 v0, 0x200000, v2
	s_nop 0
	v_cndmask_b32_e32 v92, v247, v92, vcc
	v_cmp_ne_u32_e32 vcc, 0, v0
	v_and_b32_e32 v0, 0x400000, v2
	s_nop 0
	v_cndmask_b32_e32 v13, v247, v93, vcc
	v_cmp_ne_u32_e32 vcc, 0, v0
	v_and_b32_e32 v0, 0x800000, v2
	v_mbcnt_hi_u32_b32 v2, -1, v223
	v_cndmask_b32_e32 v113, v247, v94, vcc
	v_cmp_ne_u32_e32 vcc, 0, v0
	v_and_b32_e32 v0, 1, v3
	v_and_b32_e32 v4, 64, v2
	v_cndmask_b32_e32 v14, v247, v95, vcc
	v_cmp_eq_u32_e32 vcc, 1, v0
	v_and_b32_e32 v0, 2, v3
	v_add_u32_e32 v4, 64, v4
	v_cndmask_b32_e32 v114, v247, v96, vcc
	v_cmp_ne_u32_e32 vcc, 0, v0
	v_and_b32_e32 v0, 4, v3
	s_nop 0
	v_cndmask_b32_e32 v112, v247, v97, vcc
	v_cmp_ne_u32_e32 vcc, 0, v0
	v_and_b32_e32 v0, 8, v3
	s_nop 0
	v_cndmask_b32_e32 v15, v247, v98, vcc
	v_cmp_ne_u32_e32 vcc, 0, v0
	v_and_b32_e32 v0, 16, v3
	s_nop 0
	v_cndmask_b32_e32 v80, v247, v99, vcc
	v_cmp_ne_u32_e32 vcc, 0, v0
	v_and_b32_e32 v0, 32, v3
	s_nop 0
	v_cndmask_b32_e32 v81, v247, v100, vcc
	v_cmp_ne_u32_e32 vcc, 0, v0
	v_and_b32_e32 v0, 64, v3
	s_nop 0
	v_cndmask_b32_e32 v82, v247, v101, vcc
	v_cmp_ne_u32_e32 vcc, 0, v0
	v_and_b32_e32 v0, 0x80, v3
	s_nop 0
	v_cndmask_b32_e32 v83, v247, v102, vcc
	v_cmp_ne_u32_e32 vcc, 0, v0
	v_and_b32_e32 v0, 0x10000, v3
	s_nop 0
	v_cndmask_b32_e32 v84, v247, v103, vcc
	v_cmp_ne_u32_e32 vcc, 0, v0
	v_and_b32_e32 v0, 0x20000, v3
	s_nop 0
	v_cndmask_b32_e32 v5, v247, v104, vcc
	v_cmp_ne_u32_e32 vcc, 0, v0
	v_and_b32_e32 v0, 0x40000, v3
	s_nop 0
	v_cndmask_b32_e32 v6, v247, v105, vcc
	v_cmp_ne_u32_e32 vcc, 0, v0
	v_and_b32_e32 v0, 0x80000, v3
	s_nop 0
	v_cndmask_b32_e32 v7, v247, v106, vcc
	v_cmp_ne_u32_e32 vcc, 0, v0
	v_and_b32_e32 v0, 0x100000, v3
	s_nop 0
	v_cndmask_b32_e32 v8, v247, v107, vcc
	v_cmp_ne_u32_e32 vcc, 0, v0
	v_and_b32_e32 v0, 0x200000, v3
	s_nop 0
	v_cndmask_b32_e32 v9, v247, v108, vcc
	v_cmp_ne_u32_e32 vcc, 0, v0
	v_and_b32_e32 v0, 0x400000, v3
	s_nop 0
	v_cndmask_b32_e32 v10, v247, v109, vcc
	v_cmp_ne_u32_e32 vcc, 0, v0
	v_and_b32_e32 v0, 0x800000, v3
	v_xor_b32_e32 v3, 32, v2
	v_cndmask_b32_e32 v11, v247, v110, vcc
	v_cmp_ne_u32_e32 vcc, 0, v0
	v_max3_f32 v0, v121, s58, v118
	v_max3_f32 v0, v0, v120, v119
	v_max3_f32 v0, v0, v122, v116
	v_max3_f32 v0, v0, v117, v115
	v_max3_f32 v0, v0, v85, v87
	v_max3_f32 v0, v0, v88, v91
	v_max3_f32 v0, v0, v92, v13
	v_max3_f32 v0, v0, v113, v14
	v_max3_f32 v0, v0, v114, v112
	v_max3_f32 v0, v0, v15, v80
	v_max3_f32 v0, v0, v81, v82
	v_max3_f32 v0, v0, v83, v84
	v_max3_f32 v0, v0, v5, v6
	v_cndmask_b32_e32 v12, v247, v111, vcc
	v_max3_f32 v0, v0, v7, v8
	v_cmp_lt_i32_e32 vcc, v3, v4
	v_max3_f32 v0, v0, v9, v10
	v_max3_f32 v0, v0, v11, v12
	v_cndmask_b32_e32 v86, v2, v3, vcc
	v_lshlrev_b32_e32 v86, 2, v86
	ds_bpermute_b32 v86, v86, v0
	s_waitcnt lgkmcnt(0)
	v_max3_f32 v86, v184, v0, v86
	v_sub_f32_e32 v0, v86, v184
	v_mul_f32_e32 v0, 0x3e0293ee, v0
	v_cmp_lt_f32_e32 vcc, 0x41000000, v0
	s_cbranch_vccnz .Llazy_keep_2
	v_mov_b32_e32 v86, v184

; #define MFMA32(a, b, c) __builtin_amdgcn_mfma_f32_32x32x16_bf16((a), (b), (c), 0, 0, 0)
; template <int DQK, int MODE>
; DI void attn_core(const u16* __restrict__ Qg, int ldq, const u16* __restrict__ Kg, int ldk, const u16* __restrict__ Vtg,
;                   const u64* __restrict__ maskg, int q0, float scale, char* smem, int* sflags, f32x16 (&o)[4], float& l_run) {
;     ...
;       const float msc = -m_new * sc;
;       float ls = 0.f;
; #pragma unroll
;       for (int kt = 0; kt < 2; ++kt)
; #pragma unroll
;         for (int i = 0; i < 16; ++i) {
;           float pv = __builtin_amdgcn_exp2f(__builtin_fmaf(s[kt][i], sc, msc));
;           if (MODE == 1) pv = (s[kt][i] > -1e29f) ? pv : 0.f;
;           s[kt][i] = pv;
;           ls += pv;
;         }
;     ...
; #pragma unroll
;     for (int kt = 0; kt < 2; ++kt)
; #pragma unroll
;       for (int sb = 0; sb < 2; ++sb) {
;         const bf16x8 pf = pack8(s[kt][8 * sb + 0], s[kt][8 * sb + 1], s[kt][8 * sb + 2], s[kt][8 * sb + 3],
;                                 s[kt][8 * sb + 4], s[kt][8 * sb + 5], s[kt][8 * sb + 6], s[kt][8 * sb + 7]);
; #pragma unroll
;         for (int t = 0; t < 4; ++t) {
;           const bf16x8 vf = *(const bf16x8*)(Vs + (32 * t + l31) * 72 + 32 * kt + 16 * sb + hh * 8);
;           o[t] = MFMA32(vf, pf, o[t]);
;         }
;       }
.LBB0_163:
	v_mul_f32_e32 v0, 0xbe0293ee, v86
	v_fmamk_f32 v86, v121, 0x3e0293ee, v0
	v_exp_f32_e32 v86, v86
	v_fmamk_f32 v89, v118, 0x3e0293ee, v0
	v_exp_f32_e32 v89, v89
	v_fmamk_f32 v96, v116, 0x3e0293ee, v0
	v_exp_f32_e32 v98, v96
	v_add_f32_e32 v90, 0, v86
	v_fmamk_f32 v97, v14, 0x3e0293ee, v0
	v_add_f32_e32 v93, v89, v90
	v_fmamk_f32 v90, v120, 0x3e0293ee, v0
	v_exp_f32_e32 v90, v90
	v_exp_f32_e32 v97, v97
	v_fmamk_f32 v103, v15, 0x3e0293ee, v0
	v_add_f32_e32 v94, v90, v93
	v_fmamk_f32 v93, v119, 0x3e0293ee, v0
	v_exp_f32_e32 v93, v93
	v_exp_f32_e32 v15, v103
	s_nop 0
	v_add_f32_e32 v95, v93, v94
	v_fmamk_f32 v94, v122, 0x3e0293ee, v0
	v_exp_f32_e32 v94, v94
	s_nop 1
	v_add_f32_e32 v95, v94, v95
	s_nop 0
	v_fmamk_f32 v96, v117, 0x3e0293ee, v0
	v_exp_f32_e32 v99, v96
	v_add_f32_e32 v95, v98, v95
	s_nop 0
	v_fmamk_f32 v96, v115, 0x3e0293ee, v0
	v_exp_f32_e32 v100, v96
	v_add_f32_e32 v95, v99, v95
	s_nop 0
	v_fmamk_f32 v96, v85, 0x3e0293ee, v0
	v_exp_f32_e32 v85, v96
	v_add_f32_e32 v95, v100, v95
	s_nop 0
	v_fmamk_f32 v96, v87, 0x3e0293ee, v0
	v_exp_f32_e32 v87, v96
	v_add_f32_e32 v95, v85, v95
	s_nop 0
	v_fmamk_f32 v96, v88, 0x3e0293ee, v0
	v_exp_f32_e32 v88, v96
	v_add_f32_e32 v95, v87, v95
	s_nop 0
	v_fmamk_f32 v96, v91, 0x3e0293ee, v0
	v_exp_f32_e32 v91, v96
	v_add_f32_e32 v95, v88, v95
	s_nop 0
	v_fmamk_f32 v96, v92, 0x3e0293ee, v0
	v_exp_f32_e32 v92, v96
	v_add_f32_e32 v95, v91, v95
	s_nop 0
	v_add_f32_e32 v96, v92, v95
	v_fmamk_f32 v95, v13, 0x3e0293ee, v0
	v_exp_f32_e32 v95, v95
	s_nop 1
	v_add_f32_e32 v13, v95, v96
	v_fmamk_f32 v96, v113, 0x3e0293ee, v0
	v_exp_f32_e32 v96, v96
	s_nop 1
	v_add_f32_e32 v13, v96, v13
	s_nop 0
	v_add_f32_e32 v14, v97, v13
	v_fmamk_f32 v13, v114, 0x3e0293ee, v0
	v_exp_f32_e32 v13, v13
	s_nop 1
	v_add_f32_e32 v102, v13, v14
	v_fmamk_f32 v14, v112, 0x3e0293ee, v0
	v_exp_f32_e32 v14, v14
	s_nop 1
	v_add_f32_e32 v102, v14, v102
	s_nop 0
	v_fmamk_f32 v103, v80, 0x3e0293ee, v0
	v_exp_f32_e32 v80, v103
	v_add_f32_e32 v102, v15, v102
	s_nop 0
	v_fmamk_f32 v103, v81, 0x3e0293ee, v0
	v_exp_f32_e32 v81, v103
	v_add_f32_e32 v102, v80, v102
	s_nop 0
	v_fmamk_f32 v103, v82, 0x3e0293ee, v0
	v_exp_f32_e32 v82, v103
	v_add_f32_e32 v102, v81, v102
	s_nop 0
	v_fmamk_f32 v103, v83, 0x3e0293ee, v0
	v_exp_f32_e32 v83, v103
	v_add_f32_e32 v102, v82, v102
	s_nop 0
	v_fmamk_f32 v103, v84, 0x3e0293ee, v0
	v_exp_f32_e32 v84, v103
	v_add_f32_e32 v102, v83, v102
	s_nop 0
	v_fmamk_f32 v103, v5, 0x3e0293ee, v0
	v_exp_f32_e32 v5, v103
	v_add_f32_e32 v102, v84, v102
	s_nop 0
	v_fmamk_f32 v103, v6, 0x3e0293ee, v0
	v_exp_f32_e32 v6, v103
	v_add_f32_e32 v102, v5, v102
	s_nop 0
	v_fmamk_f32 v103, v7, 0x3e0293ee, v0
	v_exp_f32_e32 v7, v103
	v_add_f32_e32 v102, v6, v102
	s_nop 0
	v_fmamk_f32 v103, v8, 0x3e0293ee, v0
	v_exp_f32_e32 v8, v103
	v_add_f32_e32 v102, v7, v102
	s_nop 0
	v_fmamk_f32 v103, v9, 0x3e0293ee, v0
	v_exp_f32_e32 v9, v103
	v_add_f32_e32 v102, v8, v102
	s_nop 0
	v_fmamk_f32 v103, v10, 0x3e0293ee, v0
	v_exp_f32_e32 v10, v103
	v_add_f32_e32 v102, v9, v102
	s_nop 0
	v_fmamk_f32 v103, v11, 0x3e0293ee, v0
	v_exp_f32_e32 v11, v103
	v_fmac_f32_e32 v0, 0x3e0293ee, v12
	v_exp_f32_e32 v12, v0
	v_add_f32_e32 v102, v10, v102
	s_nop 0
	v_add_f32_e32 v102, v11, v102
	s_nop 0
	v_add_f32_e32 v0, v12, v102
	v_cvt_pk_bf16_f32 v102, v86, v89
	v_cvt_pk_bf16_f32 v103, v90, v93
	v_cvt_pk_bf16_f32 v104, v94, v98
	v_cvt_pk_bf16_f32 v105, v99, v100
	s_nop 1
	v_add_u32_e32 v86, v174, v175
	v_add_f32_e32 v0, v0, v101
	ds_read_b128 v[110:113], v86 offset:17408
	ds_read_b128 v[114:117], v86 offset:22016
	ds_read_b128 v[118:121], v86 offset:26624
	ds_read_b128 v[122:125], v86 offset:31232
	ds_read_b128 v[126:129], v86 offset:17440
	ds_read_b128 v[130:133], v86 offset:22048
	s_waitcnt lgkmcnt(5)
	v_mfma_f32_32x32x16_bf16 v[64:79], v[110:113], v[102:105], v[64:79]
	ds_read_b128 v[110:113], v86 offset:26656
	s_waitcnt lgkmcnt(5)
	v_mfma_f32_32x32x16_bf16 v[48:63], v[114:117], v[102:105], v[48:63]
	ds_read_b128 v[114:117], v86 offset:31264
	s_waitcnt lgkmcnt(5)
	v_mfma_f32_32x32x16_bf16 v[32:47], v[118:121], v[102:105], v[32:47]
	ds_read_b128 v[118:121], v86 offset:17472
	s_waitcnt lgkmcnt(5)
	v_mfma_f32_32x32x16_bf16 v[16:31], v[122:125], v[102:105], v[16:31]
	ds_read_b128 v[122:125], v86 offset:22080
	v_cvt_pk_bf16_f32 v98, v85, v87
	v_cvt_pk_bf16_f32 v99, v88, v91
	v_cvt_pk_bf16_f32 v100, v92, v95
	v_cvt_pk_bf16_f32 v101, v96, v97
	s_nop 1
	s_waitcnt lgkmcnt(5)
	v_mfma_f32_32x32x16_bf16 v[64:79], v[126:129], v[98:101], v[64:79]
	ds_read_b128 v[126:129], v86 offset:26688
	s_waitcnt lgkmcnt(5)
	v_mfma_f32_32x32x16_bf16 v[48:63], v[130:133], v[98:101], v[48:63]
	ds_read_b128 v[130:133], v86 offset:31296
	s_waitcnt lgkmcnt(5)
	v_mfma_f32_32x32x16_bf16 v[32:47], v[110:113], v[98:101], v[32:47]
	ds_read_b128 v[110:113], v86 offset:17504
	s_waitcnt lgkmcnt(5)
	v_mfma_f32_32x32x16_bf16 v[16:31], v[114:117], v[98:101], v[16:31]
	ds_read_b128 v[114:117], v86 offset:22112
	v_cvt_pk_bf16_f32 v88, v13, v14
	v_cvt_pk_bf16_f32 v89, v15, v80
	v_cvt_pk_bf16_f32 v90, v81, v82
	v_cvt_pk_bf16_f32 v91, v83, v84
	s_nop 1
	s_waitcnt lgkmcnt(5)
	v_mfma_f32_32x32x16_bf16 v[64:79], v[118:121], v[88:91], v[64:79]
	ds_read_b128 v[118:121], v86 offset:26720
	s_waitcnt lgkmcnt(5)
	v_mfma_f32_32x32x16_bf16 v[48:63], v[122:125], v[88:91], v[48:63]
	ds_read_b128 v[122:125], v86 offset:31328
	s_waitcnt lgkmcnt(5)
	v_mfma_f32_32x32x16_bf16 v[32:47], v[126:129], v[88:91], v[32:47]
	s_waitcnt lgkmcnt(4)
	v_mfma_f32_32x32x16_bf16 v[16:31], v[130:133], v[88:91], v[16:31]
	v_cvt_pk_bf16_f32 v80, v5, v6
	v_cvt_pk_bf16_f32 v81, v7, v8
	v_cvt_pk_bf16_f32 v82, v9, v10
	v_cvt_pk_bf16_f32 v83, v11, v12
	s_nop 1
	s_waitcnt lgkmcnt(3)
	v_mfma_f32_32x32x16_bf16 v[64:79], v[110:113], v[80:83], v[64:79]
	s_waitcnt lgkmcnt(2)
	v_mfma_f32_32x32x16_bf16 v[48:63], v[114:117], v[80:83], v[48:63]
	s_waitcnt lgkmcnt(1)
	v_mfma_f32_32x32x16_bf16 v[32:47], v[118:121], v[80:83], v[32:47]
	s_waitcnt lgkmcnt(0)
	v_mfma_f32_32x32x16_bf16 v[16:31], v[122:125], v[80:83], v[16:31]
